# in-proj: tiles with gelu / head-norm epilogues spread over the workgroups of an XCD group (tile pairs swapped in rounds 2 and 3) so no workgroup gets two heavy epilogues
# baseline (speedup 1.0000x reference)
; DEVI bool tile_map(int it, int NT, int& mt, int& nt) {
;   const int x = blockIdx.x & 7, j = blockIdx.x >> 3, nxb = gridDim.x >> 3;
;   const int q = it * nxb + j;
;   if (q >= 8 * NT) return false;
;   const int band = q / (4 * NT), r = q - band * 4 * NT;
;   nt = r >> 2;
;   mt = x * 8 + band * 4 + (r & 3);
;   return true;
; }
; DEVI void phase2(const Params& p, int l, char* lds) {
;     ...
;     int mt2 = 0, nt2 = 0;
;     const bool have2 = tile_map(it + 1, 12, mt2, nt2);
.LBB0_676:
	s_add_i32 s47, s20, 1
	s_mul_i32 s25, s47, s46
	s_add_i32 s25, s25, s86
	s_sub_u32 s27, s25, 48
	s_cmp_lt_u32 s27, 32
	s_cselect_b32 s27, 8, 0
	s_xor_b32 s25, s25, s27
	s_cmpk_lt_u32 s25, 0x60
	s_cselect_b64 s[0:1], -1, 0
	s_cmpk_gt_u32 s25, 0x5f
	s_cselect_b64 s[42:43], -1, 0
	s_and_b64 vcc, exec, s[42:43]
	s_mov_b32 s48, 0
	s_mov_b32 s49, 0
	s_cbranch_vccnz .LBB0_678
	s_cmp_gt_u32 s25, 47
	s_cselect_b32 s28, 0xffffffd0, 0
	s_cselect_b32 s27, 4, 0
	s_add_i32 s28, s28, s25
	s_and_b32 s25, s25, 3
	s_or_b32 s25, s25, s27
	s_ashr_i32 s48, s28, 2
	s_or_b32 s49, s25, s87
